# v19 + per-batch mixers reordered: reta, arrive at grid barrier, attention, wait, scan (split-phase barrier over attention)
# speedup vs baseline: 1.0168x; 1.0065x over previous
; __device__ __forceinline__ unsigned xb_ld(unsigned* p)              { return __hip_atomic_load(p, __ATOMIC_RELAXED, __HIP_MEMORY_SCOPE_AGENT); }
; __device__ __forceinline__ unsigned xb_add(unsigned* p, unsigned v) { return __hip_atomic_fetch_add(p, v, __ATOMIC_RELAXED, __HIP_MEMORY_SCOPE_AGENT); }
; #define XB_SPIN(cond, bar) do { unsigned _sp = 0; while (cond) { __builtin_amdgcn_s_sleep(1); \
;     if ((++_sp & 255u) == 0u) { if (xb_ld(&(bar)[XB_TMO])) break; if (_sp > XB_SPIN_CAP) { atomicAdd(&(bar)[XB_TMO], 1u); break; } } } } while (0)
; __device__ __forceinline__ KParams kparams() { unsigned long long a = (unsigned long long)__builtin_amdgcn_kernarg_segment_ptr(); asm volatile("" : "+s"(a)); return (KParams)a; }
; __device__ __forceinline__ void xcd_barrier(const int wv, const XcdBarrier& b) {
;     ...
;         const unsigned old = xb_add(&bar[XB_XSUB(b.x)], 1u);
;         const unsigned gen = old / nloc;
;         if (old + 1u == (gen + 1u) * nloc) {
;             __builtin_amdgcn_fence(__ATOMIC_RELEASE, "agent");
;             asm volatile("s_waitcnt vmcnt(0)" ::: "memory");
;             const unsigned og = xb_add(&bar[XB_TOP], 1u);
;             const unsigned tg = og / nx;
;             if (og + 1u == (tg + 1u) * nx) xb_add(&bar[XB_TOPGEN], 1u);
;             else XB_SPIN(xb_ld(&bar[XB_TOPGEN]) == tg, bar);
;             __builtin_amdgcn_fence(__ATOMIC_ACQUIRE, "agent");
;             xb_add(&bar[XB_XGEN(b.x)], 1u);
;             asm volatile("s_waitcnt vmcnt(0)" ::: "memory");
;         } else {
;             XB_SPIN(xb_ld(&bar[XB_XGEN(b.x)]) == gen, bar);
;             __builtin_amdgcn_fence(__ATOMIC_ACQUIRE, "agent");
;             asm volatile("s_waitcnt vmcnt(0)" ::: "memory");
;         }
;     }
;     __syncthreads();
; __global__ void __launch_bounds__(512, 2) mega(Params p_unused) {
;     ...
;         {
;             KParams kp = kparams(); unsigned char* ws = kp->ws;
;             for (int j = blockIdx.x; j < 512; j += gridDim.x) reta_item(wv, lds, ldsb, WSP(bf16_t, WS_R0), WSP(bf16_t, WS_KV), j);
.LBB0_309:
	s_or_b64 exec, exec, s[2:3]
	v_add_co_u32_e32 v2, vcc, 0x2000, v2
	s_waitcnt vmcnt(0) lgkmcnt(0)
	buffer_inv sc1
	v_addc_co_u32_e32 v3, vcc, 0, v3, vcc
	flat_atomic_add v[2:3], v184 offset:1024
	s_waitcnt vmcnt(0)
.LBB0_310:
	s_or_b64 exec, exec, s[0:1]
	s_waitcnt lgkmcnt(0)
	s_barrier
.LBB0_366:
	v_readlane_b32 s2, v253, 0
	v_readlane_b32 s3, v253, 1
	s_mov_b64 s[0:1], s[56:57]
	s_andn2_b64 vcc, exec, s[2:3]
	v_cndmask_b32_e64 v1, 0, 1, s[2:3]
	v_cmp_ne_u32_e64 s[4:5], 1, v1
	s_nop 1
	v_writelane_b32 v254, s4, 22
	s_nop 1
	v_writelane_b32 v254, s5, 23
	s_cbranch_vccnz .LBB0_373
	s_load_dwordx2 s[2:3], s[0:1], 0x70
	s_mov_b32 s8, s66
	s_waitcnt lgkmcnt(0)
	s_add_u32 s0, s2, 0x8c00000
	s_addc_u32 s1, s3, 0
	s_add_u32 s6, s2, 0x4c00000
	s_addc_u32 s7, s3, 0

; #define LAS __attribute__((address_space(3)))
; #define MFMA16(a, b, c) __builtin_amdgcn_mfma_f32_16x16x32_bf16((a), (b), (c), 0, 0, 0)
; __device__ __forceinline__ void attn_stream(const int wv, LAS unsigned char* lds, unsigned ldsb, const float* __restrict__ qng, const float* __restrict__ kng, const bf16_t* __restrict__ qkvr, bf16_t* __restrict__ og, float* __restrict__ lse, ...
;     ...
;         for (int s2 = 0; s2 < 4; ++s2) qf[s2] = *(const LAS bf16x8*)(lds + QI + (16 * w + li) * PA + (32 * s2 + 8 * g) * 2);
;         f32x4 sc[10];
; #pragma unroll
;         for (int t3 = 0; t3 < 9; t3 += 3) {
;             bf16x8 kf[3][4];
; #pragma unroll
;             for (int q = 0; q < 3; ++q)
; #pragma unroll
;                 for (int s2 = 0; s2 < 4; ++s2) kf[q][s2] = *(const LAS bf16x8*)(lds + KI + (16 * (w + t3 + q) + li) * PA + (32 * s2 + 8 * g) * 2);
;             asm volatile("s_waitcnt lgkmcnt(0)" ::: "memory");
;             f32x4 a0 = (f32x4){0.f, 0.f, 0.f, 0.f}, a1 = a0, a2 = a0;
; #pragma unroll
;             for (int s2 = 0; s2 < 4; ++s2) { a0 = MFMA16(kf[0][s2], qf[s2], a0); a1 = MFMA16(kf[1][s2], qf[s2], a1); a2 = MFMA16(kf[2][s2], qf[s2], a2); }
;             sc[t3] = a0; sc[t3 + 1] = a1; sc[t3 + 2] = a2;
;         }
;         sc[9] = (f32x4){0.f, 0.f, 0.f, 0.f};
;         const float slope = exp2f(-8.0f * (float)(hh + 1) / 12.0f) * (float)dil;
;         const int qi = 16 * w + li;
;         float mx = -3.0e38f;
; #pragma unroll
;         for (int tt = 0; tt < 9; ++tt)
; #pragma unroll
;             for (int e = 0; e < 4; ++e) {
;                 const int kj = 16 * (w + tt) + 4 * g + e; const int dist = 128 + qi - kj;
;                 const bool valid = (dist >= 0) && (dist <= 128) && (n > 0 || kj >= 128);
;                 const float sv = valid ? sc[tt][e] - slope * (float)dist : -3.0e38f;
;                 sc[tt][e] = sv; mx = fmaxf(mx, sv);
.LBB0_327:
	s_or_b64 exec, exec, s[2:3]
	s_add_u32 s2, s0, 0x3300000
	s_addc_u32 s3, s1, 0
	v_writelane_b32 v254, s2, 29
	v_and_b32_e32 v1, 63, v54
	v_lshlrev_b32_e32 v52, 2, v1
	v_writelane_b32 v254, s3, 30
	s_ashr_i32 s2, s6, 6
	v_xor_b32_e32 v131, 4, v52
	v_xor_b32_e32 v132, 8, v52
	v_xor_b32_e32 v133, 16, v52
	v_xor_b32_e32 v134, 32, v52
	s_lshl_b32 s3, s2, 4
	v_lshrrev_b32_e32 v55, 2, v54
	v_xor_b32_e32 v138, 64, v52
	v_xor_b32_e32 v139, 0x80, v52
	v_lshlrev_b32_e32 v52, 3, v54
	v_or_b32_e32 v135, s3, v105
	v_and_b32_e32 v55, 12, v55
	v_and_b32_e32 v52, 24, v52
	s_add_i32 s4, 0, 0x8800
	v_add_u32_e32 v70, 0x80, v135
	v_add_u32_e32 v52, s4, v52
	v_cmp_gt_u32_e64 s[4:5], 16, v1
	v_or_b32_e32 v58, s3, v55
	v_sub_u32_e32 v66, v70, v58
	v_writelane_b32 v254, s4, 31
	s_movk_i32 s11, 0x81
	v_cmp_gt_u32_e64 s[12:13], s11, v66
	v_writelane_b32 v254, s5, 32
	v_cvt_f32_u32_e32 v140, v66
	v_writelane_b32 v254, s12, 33
	v_or_b32_e32 v66, 1, v58
	v_sub_u32_e32 v66, v70, v66
	v_writelane_b32 v254, s13, 34
	v_cmp_lt_i32_e64 s[12:13], s76, v58
	v_cvt_f32_u32_e32 v141, v66
	s_add_i32 s4, s3, 16
	v_writelane_b32 v254, s12, 35
	s_movk_i32 s10, 0x110
	v_lshlrev_b32_e32 v56, 4, v105
	v_writelane_b32 v254, s13, 36
	v_cmp_gt_u32_e64 s[12:13], s11, v66
	v_or_b32_e32 v66, 2, v58
	v_sub_u32_e32 v67, v70, v66
	v_writelane_b32 v254, s12, 37
	v_cvt_f32_u32_e32 v142, v67
	v_mul_lo_u32 v136, v135, s10
	v_writelane_b32 v254, s13, 38
	s_movk_i32 s12, 0x7e
	v_cmp_lt_i32_e64 s[14:15], s12, v58
	v_mov_b32_e32 v57, v0
	v_add_u32_e32 v2, 0, v56
	v_writelane_b32 v254, s14, 39
	v_add_u32_e32 v3, 0, v136
	v_lshl_add_u64 v[56:57], s[0:1], 0, v[56:57]
	v_writelane_b32 v254, s15, 40
	v_cmp_gt_u32_e64 s[14:15], s11, v67
	s_mov_b64 s[0:1], 0x3400000
	v_lshl_add_u64 v[106:107], v[56:57], 0, s[0:1]
	v_writelane_b32 v254, s14, 41
	v_mad_u64_u32 v[108:109], s[0:1], v130, s10, v[2:3]
	s_nop 0
	v_writelane_b32 v254, s15, 42
	v_cmp_lt_i32_e64 s[14:15], s76, v66
	v_or_b32_e32 v66, 3, v58
	v_sub_u32_e32 v67, v70, v66
	v_writelane_b32 v254, s14, 43
	v_cvt_f32_u32_e32 v143, v67
	s_add_i32 s1, s2, 2
	v_writelane_b32 v254, s15, 44
	v_cmp_gt_u32_e64 s[14:15], s11, v67
	s_lshl_b32 s5, s1, 4
	v_or_b32_e32 v56, s4, v105
	v_writelane_b32 v254, s14, 45
	v_or_b32_e32 v57, s5, v105
	s_add_i32 s6, s3, 48
	v_writelane_b32 v254, s15, 46
	v_cmp_lt_i32_e64 s[14:15], s76, v66
	v_or_b32_e32 v66, s4, v55
	v_sub_u32_e32 v67, v70, v66
	v_writelane_b32 v254, s14, 47
	v_cvt_f32_u32_e32 v144, v67
	s_add_i32 s0, s3, 64
	v_writelane_b32 v254, s15, 48
	v_cmp_gt_u32_e64 s[14:15], s11, v67
	v_xad_u32 v67, v66, -1, v70
	v_cvt_f32_u32_e32 v145, v67
	v_writelane_b32 v254, s14, 49
	s_add_i32 s7, s3, 0x50
	s_add_i32 s9, s3, 0x70
	v_writelane_b32 v254, s15, 50
	v_cmp_lt_i32_e64 s[14:15], s76, v66
	s_addk_i32 s3, 0x80
	v_or_b32_e32 v64, s3, v105
	v_writelane_b32 v254, s14, 51
	s_add_i32 s3, s2, 4
	v_lshrrev_b32_e32 v68, 2, v105
	v_writelane_b32 v254, s15, 52
	v_cmp_gt_u32_e64 s[14:15], s11, v67
	v_or_b32_e32 v67, 2, v66
	v_sub_u32_e32 v69, v70, v67
	v_writelane_b32 v254, s14, 53
	v_cvt_f32_u32_e32 v146, v69
	v_or3_b32 v65, v55, v68, 16
	v_writelane_b32 v254, s15, 54
	v_cmp_lt_i32_e64 s[14:15], s12, v66
	v_or_b32_e32 v66, 3, v66
	v_and_b32_e32 v53, 48, v54
	v_writelane_b32 v254, s14, 55
	v_or_b32_e32 v60, s0, v105
	s_add_i32 s0, s2, 6
	v_writelane_b32 v254, s15, 56
	v_cmp_gt_u32_e64 s[14:15], s11, v69
	s_lshl_b32 s8, s0, 4
	v_lshlrev_b32_e32 v200, 2, v55
	v_writelane_b32 v254, s14, 57
	v_or_b32_e32 v59, s6, v105
	v_or_b32_e32 v61, s7, v105
	v_writelane_b32 v254, s15, 58
	v_cmp_lt_i32_e64 s[14:15], s76, v67
	v_sub_u32_e32 v67, v70, v66
	v_cvt_f32_u32_e32 v147, v67
	v_writelane_b32 v254, s14, 59
	v_or_b32_e32 v62, s8, v105
	v_or_b32_e32 v63, s9, v105
	v_writelane_b32 v254, s15, 60
	v_cmp_gt_u32_e64 s[14:15], s11, v67
	v_add_u32_e32 v137, 0, v53
	v_mad_i32_i24 v1, v105, -14, v2
	v_writelane_b32 v254, s14, 61
	v_mul_lo_u32 v56, v56, s10
	v_mul_lo_u32 v57, v57, s10
	v_writelane_b32 v254, s15, 62
	v_cmp_lt_i32_e64 s[14:15], s76, v66
	v_or_b32_e32 v66, s5, v55
	v_sub_u32_e32 v67, v70, v66
	v_writelane_b32 v254, s14, 63
	v_cmp_gt_u32_e64 s[4:5], s11, v67
	v_cvt_f32_u32_e32 v148, v67
	v_writelane_b32 v252, s15, 0
	v_writelane_b32 v252, s4, 62
	v_xad_u32 v67, v66, -1, v70
	v_cvt_f32_u32_e32 v149, v67
	v_writelane_b32 v252, s5, 63
	v_cmp_lt_i32_e64 s[4:5], s76, v66
	v_mul_lo_u32 v59, v59, s10
	v_mul_lo_u32 v60, v60, s10
	v_writelane_b32 v252, s4, 1
	v_mul_lo_u32 v61, v61, s10
	v_mul_lo_u32 v62, v62, s10
	v_writelane_b32 v252, s5, 2
	v_cmp_gt_u32_e64 s[4:5], s11, v67
	v_or_b32_e32 v67, 2, v66
	v_sub_u32_e32 v69, v70, v67
	v_writelane_b32 v252, s4, 3
	v_cvt_f32_u32_e32 v150, v69
	v_mul_lo_u32 v63, v63, s10
	v_writelane_b32 v252, s5, 4
	v_cmp_lt_i32_e64 s[4:5], s12, v66
	v_or_b32_e32 v66, 3, v66
	v_mul_lo_u32 v64, v64, s10
	v_writelane_b32 v252, s4, 5
	v_lshlrev_b32_e32 v104, 3, v105
	v_add_u32_e32 v109, 0x8800, v108
	v_writelane_b32 v252, s5, 6
	v_cmp_gt_u32_e64 s[4:5], s11, v69
	v_or_b32_e32 v201, 4, v200
	v_or_b32_e32 v202, 8, v200
	v_writelane_b32 v252, s4, 7
	v_or_b32_e32 v203, 12, v200
	v_add_u32_e32 v207, v3, v53
	v_writelane_b32 v252, s5, 8
	v_cmp_lt_i32_e64 s[4:5], s76, v67
	v_sub_u32_e32 v67, v70, v66
	v_cvt_f32_u32_e32 v151, v67
	v_writelane_b32 v252, s4, 9
	v_add_u32_e32 v208, v137, v56
	v_add_u32_e32 v209, v137, v57
	v_writelane_b32 v252, s5, 10
	v_cmp_gt_u32_e64 s[4:5], s11, v67
	v_add_u32_e32 v210, v137, v59
	v_add_u32_e32 v211, v137, v60
	v_writelane_b32 v252, s4, 11
	v_add_u32_e32 v212, v137, v61
	v_add_u32_e32 v213, v137, v62
	v_writelane_b32 v252, s5, 12
	v_cmp_lt_i32_e64 s[4:5], s76, v66
	v_or_b32_e32 v66, s6, v55
; #define LAS __attribute__((address_space(3)))
; #define MFMA16(a, b, c) __builtin_amdgcn_mfma_f32_16x16x32_bf16((a), (b), (c), 0, 0, 0)
; __device__ __forceinline__ void attn_stream(const int wv, LAS unsigned char* lds, unsigned ldsb, const float* __restrict__ qng, const float* __restrict__ kng, const bf16_t* __restrict__ qkvr, bf16_t* __restrict__ og, float* __restrict__ lse, ...
;     ...
;         for (int s2 = 0; s2 < 4; ++s2) qf[s2] = *(const LAS bf16x8*)(lds + QI + (16 * w + li) * PA + (32 * s2 + 8 * g) * 2);
;         f32x4 sc[10];
; #pragma unroll
;         for (int t3 = 0; t3 < 9; t3 += 3) {
;             bf16x8 kf[3][4];
; #pragma unroll
;             for (int q = 0; q < 3; ++q)
; #pragma unroll
;                 for (int s2 = 0; s2 < 4; ++s2) kf[q][s2] = *(const LAS bf16x8*)(lds + KI + (16 * (w + t3 + q) + li) * PA + (32 * s2 + 8 * g) * 2);
;             asm volatile("s_waitcnt lgkmcnt(0)" ::: "memory");
;             f32x4 a0 = (f32x4){0.f, 0.f, 0.f, 0.f}, a1 = a0, a2 = a0;
; #pragma unroll
;             for (int s2 = 0; s2 < 4; ++s2) { a0 = MFMA16(kf[0][s2], qf[s2], a0); a1 = MFMA16(kf[1][s2], qf[s2], a1); a2 = MFMA16(kf[2][s2], qf[s2], a2); }
;             sc[t3] = a0; sc[t3 + 1] = a1; sc[t3 + 2] = a2;
;         }
;         sc[9] = (f32x4){0.f, 0.f, 0.f, 0.f};
;         const float slope = exp2f(-8.0f * (float)(hh + 1) / 12.0f) * (float)dil;
;         const int qi = 16 * w + li;
;         float mx = -3.0e38f;
; #pragma unroll
;         for (int tt = 0; tt < 9; ++tt)
; #pragma unroll
;             for (int e = 0; e < 4; ++e) {
;                 const int kj = 16 * (w + tt) + 4 * g + e; const int dist = 128 + qi - kj;
;                 const bool valid = (dist >= 0) && (dist <= 128) && (n > 0 || kj >= 128);
;                 const float sv = valid ? sc[tt][e] - slope * (float)dist : -3.0e38f;
;                 sc[tt][e] = sv; mx = fmaxf(mx, sv);
	v_sub_u32_e32 v67, v70, v66
	v_writelane_b32 v252, s4, 13
	v_cvt_f32_u32_e32 v152, v67
	v_add_u32_e32 v214, v137, v63
	v_writelane_b32 v252, s5, 14
	v_cmp_gt_u32_e64 s[4:5], s11, v67
	v_xad_u32 v67, v66, -1, v70
	v_cvt_f32_u32_e32 v153, v67
	v_writelane_b32 v252, s4, 15
	v_add_u32_e32 v215, v137, v64
	v_readlane_b32 s39, v253, 49
	v_writelane_b32 v252, s5, 16
	v_cmp_lt_i32_e64 s[4:5], s76, v66
	s_mov_b32 s82, s66
	s_nop 0
	v_writelane_b32 v252, s4, 17
	s_nop 1
	v_writelane_b32 v252, s5, 18
	v_cmp_gt_u32_e64 s[4:5], s11, v67
	v_or_b32_e32 v67, 2, v66
	v_sub_u32_e32 v69, v70, v67
	v_writelane_b32 v252, s4, 19
	v_cvt_f32_u32_e32 v154, v69
	s_nop 0
	v_writelane_b32 v252, s5, 20
	v_cmp_lt_i32_e64 s[4:5], s12, v66
	v_or_b32_e32 v66, 3, v66
	s_nop 0
	v_writelane_b32 v252, s4, 21
	s_nop 1
	v_writelane_b32 v252, s5, 22
	v_cmp_gt_u32_e64 s[4:5], s11, v69
	s_nop 1
	v_writelane_b32 v252, s4, 23
	s_nop 1
	v_writelane_b32 v252, s5, 24
	v_cmp_lt_i32_e64 s[4:5], s76, v67
	v_sub_u32_e32 v67, v70, v66
	v_cvt_f32_u32_e32 v155, v67
	v_writelane_b32 v252, s4, 25
	s_nop 1
	v_writelane_b32 v252, s5, 26
	v_cmp_gt_u32_e64 s[4:5], s11, v67
	v_lshl_or_b32 v67, s3, 4, v55
	v_or_b32_e32 v69, 2, v67
	v_writelane_b32 v252, s4, 27
	v_sub_u32_e32 v71, v70, v69
	v_cvt_f32_u32_e32 v158, v71
	v_writelane_b32 v252, s5, 28
	v_cmp_lt_i32_e64 s[4:5], s76, v66
	v_sub_u32_e32 v66, v70, v67
	v_cvt_f32_u32_e32 v156, v66
	v_writelane_b32 v252, s4, 29
	s_nop 1
	v_writelane_b32 v252, s5, 30
	v_cmp_gt_u32_e64 s[4:5], s11, v66
	v_xad_u32 v66, v67, -1, v70
	v_cvt_f32_u32_e32 v157, v66
	v_writelane_b32 v252, s4, 31
	s_nop 1
	v_writelane_b32 v252, s5, 32
	v_cmp_lt_i32_e64 s[4:5], s76, v67
	s_nop 1
	v_writelane_b32 v252, s4, 33
	s_nop 1
	v_writelane_b32 v252, s5, 34
	v_cmp_gt_u32_e64 s[4:5], s11, v66
	v_or_b32_e32 v66, s7, v55
	v_or_b32_e32 v80, 2, v66
	v_writelane_b32 v252, s4, 35
	v_or_b32_e32 v82, 3, v66
	v_sub_u32_e32 v81, v70, v80
	v_writelane_b32 v252, s5, 36
	v_cmp_lt_i32_e64 s[4:5], s12, v67
	v_sub_u32_e32 v83, v70, v82
	v_cvt_f32_u32_e32 v162, v81
	v_writelane_b32 v252, s4, 37
	v_cvt_f32_u32_e32 v163, v83
	v_cmp_lt_i32_e64 s[28:29], s76, v66
	v_writelane_b32 v252, s5, 38
	v_cmp_gt_u32_e64 s[4:5], s11, v71
	v_or_b32_e32 v71, 3, v67
	v_or_b32_e32 v67, s8, v55
	v_writelane_b32 v252, s4, 39
	v_sub_u32_e32 v72, v70, v71
	v_or_b32_e32 v86, 2, v67
	v_writelane_b32 v252, s5, 40
	v_cmp_lt_i32_e64 s[4:5], s76, v69
	v_or_b32_e32 v69, s9, v55
	v_or_b32_e32 v88, 3, v67
	v_writelane_b32 v252, s4, 41
	v_or_b32_e32 v92, 2, v69
	v_or_b32_e32 v94, 3, v69
	v_writelane_b32 v252, s5, 42
	s_min_i32 s4, s2, 15
	s_lshl_b32 s4, s4, 4
	v_or3_b32 v73, s4, v68, v55
	s_min_i32 s4, s1, 15
	s_min_i32 s1, s1, 14
	v_lshl_add_u32 v76, s1, 4, v65
	s_min_i32 s1, s3, 15
	s_min_i32 s5, s2, 14
	s_lshl_b32 s4, s4, 4
	s_min_i32 s3, s3, 14
	s_lshl_b32 s1, s1, 4
	v_lshl_add_u32 v74, s5, 4, v65
	v_or3_b32 v75, s4, v68, v55
	v_or3_b32 v77, s1, v68, v55
	v_lshl_add_u32 v78, s3, 4, v65
	s_min_i32 s1, s0, 15
	s_add_i32 s4, s2, 8
	v_mad_u64_u32 v[110:111], s[2:3], v73, s10, v[52:53]
	v_mad_u64_u32 v[112:113], s[2:3], v74, s10, v[52:53]
	v_mad_u64_u32 v[114:115], s[2:3], v75, s10, v[52:53]
	v_mad_u64_u32 v[116:117], s[2:3], v76, s10, v[52:53]
	v_mad_u64_u32 v[118:119], s[2:3], v77, s10, v[52:53]
	v_mad_u64_u32 v[120:121], s[2:3], v78, s10, v[52:53]
	s_lshl_b32 s1, s1, 4
	s_min_i32 s2, s0, 14
	v_or3_b32 v79, s1, v68, v55
	v_lshl_add_u32 v73, s2, 4, v65
	v_mad_u64_u32 v[122:123], s[0:1], v79, s10, v[52:53]
	v_mad_u64_u32 v[124:125], s[0:1], v73, s10, v[52:53]
	v_lshl_or_b32 v96, s4, 4, v55
	s_min_i32 s0, s4, 15
; __device__ __forceinline__ void attn_stream(const int wv, LAS unsigned char* lds, unsigned ldsb, const float* __restrict__ qng, const float* __restrict__ kng, const bf16_t* __restrict__ qkvr, bf16_t* __restrict__ og, float* __restrict__ lse, ...
;     ...
;         const int qi = 16 * w + li;
;         float mx = -3.0e38f;
; #pragma unroll
;         for (int tt = 0; tt < 9; ++tt)
; #pragma unroll
;             for (int e = 0; e < 4; ++e) {
;                 const int kj = 16 * (w + tt) + 4 * g + e; const int dist = 128 + qi - kj;
;                 const bool valid = (dist >= 0) && (dist <= 128) && (n > 0 || kj >= 128);
;                 const float sv = valid ? sc[tt][e] - slope * (float)dist : -3.0e38f;
;                 sc[tt][e] = sv; mx = fmaxf(mx, sv);
;     ...
;         const int q4 = li >> 2, p4 = lane & 3;
; #pragma unroll
;         for (int u = 0; u < 5; ++u) {
;             int kt0 = w + 2 * u, kt1 = w + 2 * u + 1; kt0 = kt0 > 15 ? 15 : kt0; kt1 = kt1 > 15 ? 15 : kt1;
;             const unsigned a0 = ldsb + KI + (16 * kt0 + 4 * g + q4) * PA + 8 * p4;
;             const unsigned a1 = ldsb + KI + (16 * kt1 + 4 * g + q4) * PA + 8 * p4;
	v_or_b32_e32 v99, 2, v96
	v_or_b32_e32 v101, 3, v96
	s_min_i32 s2, s4, 14
	s_lshl_b32 s0, s0, 4
	v_cmp_gt_u32_e64 s[22:23], s11, v72
	v_cmp_lt_i32_e64 s[24:25], s76, v71
	v_cvt_f32_u32_e32 v159, v72
	v_sub_u32_e32 v71, v70, v66
	v_xad_u32 v72, v66, -1, v70
	v_sub_u32_e32 v84, v70, v67
	v_xad_u32 v85, v67, -1, v70
	v_sub_u32_e32 v87, v70, v86
	v_sub_u32_e32 v89, v70, v88
	v_sub_u32_e32 v90, v70, v69
	v_xad_u32 v91, v69, -1, v70
	v_sub_u32_e32 v93, v70, v92
	v_sub_u32_e32 v95, v70, v94
	v_sub_u32_e32 v97, v70, v96
	v_xad_u32 v98, v96, -1, v70
	v_sub_u32_e32 v100, v70, v99
	v_sub_u32_e32 v70, v70, v101
	v_or3_b32 v68, s0, v68, v55
	v_lshl_add_u32 v65, s2, 4, v65
	v_cvt_f32_u32_e32 v160, v71
	v_cvt_f32_u32_e32 v161, v72
	v_cvt_f32_u32_e32 v164, v84
	v_cvt_f32_u32_e32 v165, v85
	v_cvt_f32_u32_e32 v166, v87
	v_cvt_f32_u32_e32 v167, v89
	v_cvt_f32_u32_e32 v168, v90
	v_cvt_f32_u32_e32 v169, v91
	v_cvt_f32_u32_e32 v170, v93
	v_cvt_f32_u32_e32 v171, v95
	v_cvt_f32_u32_e32 v172, v97
	v_cvt_f32_u32_e32 v173, v98
	v_cvt_f32_u32_e32 v174, v100
	v_cvt_f32_u32_e32 v175, v70
	v_mad_u64_u32 v[126:127], s[0:1], v68, s10, v[52:53]
	v_mad_u64_u32 v[128:129], s[0:1], v65, s10, v[52:53]
	v_mul_lo_u32 v52, v58, s10
	v_add_u32_e32 v55, 0x200, v54
	v_add_u32_e32 v58, 0x400, v54
	v_add_u32_e32 v54, 0x600, v54
	v_ashrrev_i32_e32 v204, 4, v55
	v_ashrrev_i32_e32 v205, 4, v58
	v_ashrrev_i32_e32 v206, 4, v54
	v_mul_lo_u32 v55, v204, s10
	v_mul_lo_u32 v58, v205, s10
	v_mul_lo_u32 v54, v206, s10
	s_movk_i32 s10, 0x7f
	v_add_u32_e32 v111, 64, v124
	v_add_u32_e32 v113, 0x60, v122
	v_add_u32_e32 v115, 0x60, v124
	v_add_u32_e32 v117, 0x80, v122
	v_add_u32_e32 v119, 0x80, v124
	v_add_u32_e32 v121, 0xa0, v122
	v_add_u32_e32 v123, 0xa0, v124
	v_add_u32_e32 v125, 0xc0, v122
	v_add_u32_e32 v176, 0xc0, v124
	v_add_u32_e32 v177, 0xe0, v122
	v_add_u32_e32 v180, 0xe0, v124
	v_add_u32_e32 v127, 32, v126
	v_add_u32_e32 v129, 32, v128
	v_add_u32_e32 v181, 64, v126
	v_add_u32_e32 v182, 64, v128
	v_add_u32_e32 v183, 0x60, v126
	v_add_u32_e32 v191, 0x60, v128
	v_add_u32_e32 v192, 0x80, v126
	v_add_u32_e32 v193, 0x80, v128
	v_add_u32_e32 v194, 0xa0, v126
	v_add_u32_e32 v195, 0xa0, v128
	v_add_u32_e32 v196, 0xc0, v126
	v_add_u32_e32 v197, 0xc0, v128
	v_add_u32_e32 v198, 0xe0, v126
	v_add_u32_e32 v199, 0xe0, v128
	v_add_u32_e32 v216, v1, v52
	v_add_u32_e32 v217, v2, v55
	v_add_u32_e32 v218, v2, v58
	v_add_u32_e32 v219, v2, v54
	v_cmp_gt_u32_e64 s[26:27], s11, v71
	v_cmp_gt_u32_e64 s[30:31], s11, v72
	v_cmp_lt_i32_e64 s[34:35], s12, v66
	v_cmp_gt_u32_e64 s[14:15], s11, v81
	v_cmp_lt_i32_e64 s[4:5], s76, v80
	v_cmp_gt_u32_e64 s[0:1], s11, v83
	v_cmp_lt_i32_e64 s[2:3], s76, v82
	v_cmp_gt_u32_e64 s[6:7], s11, v84
	v_cmp_lt_i32_e64 s[8:9], s76, v67
	v_cmp_gt_u32_e64 s[16:17], s11, v85
	v_cmp_lt_i32_e64 s[40:41], s12, v67
	v_cmp_gt_u32_e64 s[42:43], s11, v87
	v_cmp_lt_i32_e64 s[44:45], s76, v86
	v_cmp_gt_u32_e64 s[46:47], s11, v89
	v_cmp_lt_i32_e64 s[48:49], s76, v88
	v_cmp_gt_u32_e64 s[50:51], s11, v90
	v_cmp_lt_i32_e64 s[52:53], s76, v69
	v_cmp_gt_u32_e64 s[54:55], s11, v91
	v_cmp_lt_i32_e64 s[56:57], s12, v69
	v_cmp_gt_u32_e64 s[58:59], s11, v93
	v_cmp_lt_i32_e64 s[60:61], s76, v92
	v_cmp_gt_u32_e64 s[62:63], s11, v95
	v_cmp_lt_i32_e64 s[64:65], s76, v94
	v_cmp_gt_u32_e64 s[66:67], s11, v97
	v_cmp_lt_i32_e64 s[68:69], s76, v96
	v_cmp_gt_u32_e64 s[70:71], s11, v98
	v_cmp_lt_i32_e64 s[72:73], s12, v96
	v_cmp_gt_u32_e64 s[74:75], s11, v100
	v_cmp_lt_i32_e64 s[76:77], s76, v99
	v_cmp_gt_u32_e64 s[78:79], s11, v70
	v_cmp_lt_i32_e64 s[80:81], s10, v101
	s_branch .LBB0_329

; #define LAS __attribute__((address_space(3)))
; #define MFMA16(a, b, c) __builtin_amdgcn_mfma_f32_16x16x32_bf16((a), (b), (c), 0, 0, 0)
; __device__ __forceinline__ void attn_stream(const int wv, LAS unsigned char* lds, unsigned ldsb, const float* __restrict__ qng, const float* __restrict__ kng, const bf16_t* __restrict__ qkvr, bf16_t* __restrict__ og, float* __restrict__ lse, ...
;     ...
;         f32x4 sc[10];
; #pragma unroll
;         for (int t3 = 0; t3 < 9; t3 += 3) {
;             bf16x8 kf[3][4];
; #pragma unroll
;             for (int q = 0; q < 3; ++q)
; #pragma unroll
;                 for (int s2 = 0; s2 < 4; ++s2) kf[q][s2] = *(const LAS bf16x8*)(lds + KI + (16 * (w + t3 + q) + li) * PA + (32 * s2 + 8 * g) * 2);
;             asm volatile("s_waitcnt lgkmcnt(0)" ::: "memory");
;             f32x4 a0 = (f32x4){0.f, 0.f, 0.f, 0.f}, a1 = a0, a2 = a0;
; #pragma unroll
;             for (int s2 = 0; s2 < 4; ++s2) { a0 = MFMA16(kf[0][s2], qf[s2], a0); a1 = MFMA16(kf[1][s2], qf[s2], a1); a2 = MFMA16(kf[2][s2], qf[s2], a2); }
;             sc[t3] = a0; sc[t3 + 1] = a1; sc[t3 + 2] = a2;
;         }
;         sc[9] = (f32x4){0.f, 0.f, 0.f, 0.f};
;         const float slope = exp2f(-8.0f * (float)(hh + 1) / 12.0f) * (float)dil;
;         const int qi = 16 * w + li;
;         float mx = -3.0e38f;
; #pragma unroll
;         for (int tt = 0; tt < 9; ++tt)
; #pragma unroll
;             for (int e = 0; e < 4; ++e) {
;                 const int kj = 16 * (w + tt) + 4 * g + e; const int dist = 128 + qi - kj;
;                 const bool valid = (dist >= 0) && (dist <= 128) && (n > 0 || kj >= 128);
;                 const float sv = valid ? sc[tt][e] - slope * (float)dist : -3.0e38f;
;                 sc[tt][e] = sv; mx = fmaxf(mx, sv);
.LBB0_345:
	s_or_b64 exec, exec, s[12:13]
	s_and_b64 s[12:13], s[96:97], exec
	s_cselect_b32 s12, 4, 16
	s_and_b64 s[10:11], s[10:11], exec
	s_cselect_b32 s12, 1, s12
	s_add_i32 s10, s94, 1
	v_cvt_f32_i32_e32 v1, s10
	s_mov_b32 s13, 0x41400000
	v_readlane_b32 s96, v254, 33
	v_readlane_b32 s97, v254, 34
	v_mul_f32_e32 v1, 0xc1000000, v1
	v_div_scale_f32 v2, s[10:11], s13, s13, v1
	v_rcp_f32_e32 v3, v2
	s_mov_b32 s10, 0xc2fc0000
	v_fma_f32 v84, -v2, v3, 1.0
	v_fmac_f32_e32 v3, v84, v3
	v_div_scale_f32 v84, vcc, v1, s13, v1
	v_mul_f32_e32 v85, v84, v3
	v_fma_f32 v86, -v2, v85, v84
	v_fmac_f32_e32 v85, v86, v3
	v_fma_f32 v2, -v2, v85, v84
	v_div_fmas_f32 v2, v2, v3, v85
	v_div_fixup_f32 v1, v2, s13, v1
	v_cmp_gt_f32_e32 vcc, s10, v1
	s_and_b64 s[10:11], vcc, exec
	s_cselect_b32 s10, 0xffffffc0, 0
	v_cndmask_b32_e32 v2, 0, v187, vcc
	v_add_f32_e32 v1, v1, v2
	v_add_u32_e32 v2, v137, v136
	ds_read_b128 v[84:87], v2 offset:34816
	ds_read_b128 v[96:99], v207
	ds_read_b128 v[100:103], v2 offset:34880
	ds_read_b128 v[92:95], v207 offset:64
	s_waitcnt lgkmcnt(2)
	v_mfma_f32_16x16x32_bf16 v[84:87], v[84:87], v[96:99], 0
	ds_read_b128 v[222:225], v2 offset:34944
	ds_read_b128 v[88:91], v207 offset:128
	v_exp_f32_e32 v1, v1
	v_cvt_f32_ubyte0_e32 v3, s12
	s_waitcnt lgkmcnt(2)
	v_mfma_f32_16x16x32_bf16 v[84:87], v[100:103], v[92:95], v[84:87]
	ds_read_b128 v[100:103], v2 offset:35008
	v_ldexp_f32 v1, v1, s10
	s_cmp_lg_u32 s95, 0
	s_waitcnt lgkmcnt(1)
	v_mfma_f32_16x16x32_bf16 v[222:225], v[222:225], v[88:91], v[84:87]
	ds_read_b128 v[226:229], v208 offset:34880
	v_readlane_b32 s12, v254, 35
	s_cselect_b64 s[10:11], -1, 0
	ds_read_b128 v[84:87], v207 offset:192
	s_waitcnt lgkmcnt(0)
	v_mfma_f32_16x16x32_bf16 v[222:225], v[100:103], v[84:87], v[222:225]
	v_mul_f32_e32 v101, v1, v3
	v_readlane_b32 s13, v254, 36
	s_or_b64 s[12:13], s[12:13], s[10:11]
	s_nop 4
	v_fma_f32 v1, -v101, v140, v222
	v_fma_f32 v2, -v101, v141, v223
	v_fma_f32 v3, -v101, v142, v224
	v_fma_f32 v100, -v101, v143, v225
	ds_read_b128 v[222:225], v208 offset:34816
	s_waitcnt lgkmcnt(0)
	v_mfma_f32_16x16x32_bf16 v[222:225], v[222:225], v[96:99], 0
	s_and_b64 vcc, s[96:97], s[12:13]
	v_readlane_b32 s12, v254, 39
	v_readlane_b32 s13, v254, 40
	v_mfma_f32_16x16x32_bf16 v[222:225], v[226:229], v[92:95], v[222:225]
	ds_read_b128 v[226:229], v208 offset:34944
	v_readlane_b32 s96, v254, 37
	s_or_b64 s[12:13], s[12:13], s[10:11]
	s_waitcnt lgkmcnt(0)
	v_mfma_f32_16x16x32_bf16 v[222:225], v[226:229], v[88:91], v[222:225]
	ds_read_b128 v[226:229], v208 offset:35008
	v_readlane_b32 s97, v254, 38
	v_cndmask_b32_e32 v1, v188, v1, vcc
	s_and_b64 vcc, s[96:97], s[12:13]
	v_readlane_b32 s12, v254, 43
	v_readlane_b32 s13, v254, 44
	v_readlane_b32 s96, v254, 41
	s_or_b64 s[12:13], s[12:13], s[10:11]
	v_readlane_b32 s97, v254, 42
	v_cndmask_b32_e32 v2, v188, v2, vcc
	s_and_b64 vcc, s[96:97], s[12:13]
	v_readlane_b32 s12, v254, 47
	v_readlane_b32 s13, v254, 48
	v_readlane_b32 s96, v254, 45
	s_or_b64 s[12:13], s[12:13], s[10:11]
	v_readlane_b32 s97, v254, 46
	v_cndmask_b32_e32 v3, v188, v3, vcc
	s_and_b64 vcc, s[96:97], s[12:13]
	v_readlane_b32 s12, v254, 51
	s_waitcnt lgkmcnt(0)
	v_mfma_f32_16x16x32_bf16 v[222:225], v[226:229], v[84:87], v[222:225]
	v_readlane_b32 s13, v254, 52
	v_readlane_b32 s96, v254, 49
	s_or_b64 s[12:13], s[12:13], s[10:11]
	v_readlane_b32 s97, v254, 50
	v_cndmask_b32_e32 v100, v188, v100, vcc
	s_and_b64 vcc, s[96:97], s[12:13]
	v_readlane_b32 s12, v254, 55
	v_readlane_b32 s13, v254, 56
	v_readlane_b32 s96, v254, 53
	v_fma_f32 v102, -v101, v144, v222
	s_or_b64 s[12:13], s[12:13], s[10:11]
	v_readlane_b32 s97, v254, 54
	v_cndmask_b32_e32 v102, v188, v102, vcc
	s_and_b64 vcc, s[96:97], s[12:13]
	v_readlane_b32 s12, v254, 59
	v_readlane_b32 s13, v254, 60
	v_readlane_b32 s96, v254, 57
	v_fma_f32 v103, -v101, v145, v223
	s_or_b64 s[12:13], s[12:13], s[10:11]
	v_readlane_b32 s97, v254, 58
	v_cndmask_b32_e32 v103, v188, v103, vcc
	v_fma_f32 v221, -v101, v146, v224
	s_and_b64 vcc, s[96:97], s[12:13]
	v_cndmask_b32_e32 v222, v188, v221, vcc
	v_fma_f32 v221, -v101, v147, v225
	ds_read_b128 v[224:227], v209 offset:34816
	ds_read_b128 v[228:231], v209 offset:34880
	s_waitcnt lgkmcnt(1)
	v_mfma_f32_16x16x32_bf16 v[224:227], v[224:227], v[96:99], 0
	v_readlane_b32 s12, v254, 63
	v_readlane_b32 s13, v252, 0
	v_readlane_b32 s96, v254, 61
	s_waitcnt lgkmcnt(0)
	v_mfma_f32_16x16x32_bf16 v[224:227], v[228:231], v[92:95], v[224:227]
	ds_read_b128 v[228:231], v209 offset:34944
	s_or_b64 s[12:13], s[12:13], s[10:11]
	v_readlane_b32 s97, v254, 62
	s_waitcnt lgkmcnt(0)
	v_mfma_f32_16x16x32_bf16 v[224:227], v[228:231], v[88:91], v[224:227]
	ds_read_b128 v[228:231], v209 offset:35008
	s_waitcnt lgkmcnt(0)
	ds_read_b128 v[232:235], v210 offset:34880
	s_waitcnt lgkmcnt(1)
	v_mfma_f32_16x16x32_bf16 v[224:227], v[228:231], v[84:87], v[224:227]
	ds_read_b128 v[228:231], v210 offset:34816
	s_and_b64 vcc, s[96:97], s[12:13]
	v_readlane_b32 s12, v252, 1
	s_waitcnt lgkmcnt(0)
	v_mfma_f32_16x16x32_bf16 v[228:231], v[228:231], v[96:99], 0
	v_readlane_b32 s13, v252, 2
	v_readlane_b32 s96, v252, 62
	s_or_b64 s[12:13], s[12:13], s[10:11]
	v_mfma_f32_16x16x32_bf16 v[228:231], v[232:235], v[92:95], v[228:231]
	ds_read_b128 v[232:235], v210 offset:34944
	v_readlane_b32 s97, v252, 63
	v_cndmask_b32_e32 v223, v188, v221, vcc
	s_and_b64 vcc, s[96:97], s[12:13]
	v_readlane_b32 s12, v252, 5
	v_readlane_b32 s13, v252, 6
	v_readlane_b32 s96, v252, 3
	s_waitcnt lgkmcnt(0)
; #define LAS __attribute__((address_space(3)))
; #define MFMA16(a, b, c) __builtin_amdgcn_mfma_f32_16x16x32_bf16((a), (b), (c), 0, 0, 0)
; __device__ __forceinline__ void attn_stream(const int wv, LAS unsigned char* lds, unsigned ldsb, const float* __restrict__ qng, const float* __restrict__ kng, const bf16_t* __restrict__ qkvr, bf16_t* __restrict__ og, float* __restrict__ lse, ...
;     ...
;         f32x4 sc[10];
; #pragma unroll
;         for (int t3 = 0; t3 < 9; t3 += 3) {
;             bf16x8 kf[3][4];
; #pragma unroll
;             for (int q = 0; q < 3; ++q)
; #pragma unroll
;                 for (int s2 = 0; s2 < 4; ++s2) kf[q][s2] = *(const LAS bf16x8*)(lds + KI + (16 * (w + t3 + q) + li) * PA + (32 * s2 + 8 * g) * 2);
;             asm volatile("s_waitcnt lgkmcnt(0)" ::: "memory");
;             f32x4 a0 = (f32x4){0.f, 0.f, 0.f, 0.f}, a1 = a0, a2 = a0;
; #pragma unroll
;             for (int s2 = 0; s2 < 4; ++s2) { a0 = MFMA16(kf[0][s2], qf[s2], a0); a1 = MFMA16(kf[1][s2], qf[s2], a1); a2 = MFMA16(kf[2][s2], qf[s2], a2); }
;             sc[t3] = a0; sc[t3 + 1] = a1; sc[t3 + 2] = a2;
;         }
;         sc[9] = (f32x4){0.f, 0.f, 0.f, 0.f};
;         const float slope = exp2f(-8.0f * (float)(hh + 1) / 12.0f) * (float)dil;
;         const int qi = 16 * w + li;
;         float mx = -3.0e38f;
; #pragma unroll
;         for (int tt = 0; tt < 9; ++tt)
; #pragma unroll
;             for (int e = 0; e < 4; ++e) {
;                 const int kj = 16 * (w + tt) + 4 * g + e; const int dist = 128 + qi - kj;
;                 const bool valid = (dist >= 0) && (dist <= 128) && (n > 0 || kj >= 128);
;                 const float sv = valid ? sc[tt][e] - slope * (float)dist : -3.0e38f;
;                 sc[tt][e] = sv; mx = fmaxf(mx, sv);
	v_mfma_f32_16x16x32_bf16 v[228:231], v[232:235], v[88:91], v[228:231]
	ds_read_b128 v[232:235], v210 offset:35008
	v_fma_f32 v221, -v101, v148, v224
	s_or_b64 s[12:13], s[12:13], s[10:11]
	v_readlane_b32 s97, v252, 4
	v_cndmask_b32_e32 v224, v188, v221, vcc
	s_and_b64 vcc, s[96:97], s[12:13]
	v_readlane_b32 s12, v252, 9
	v_readlane_b32 s13, v252, 10
	v_readlane_b32 s96, v252, 7
	v_fma_f32 v221, -v101, v149, v225
	s_or_b64 s[12:13], s[12:13], s[10:11]
	v_readlane_b32 s97, v252, 8
	v_cndmask_b32_e32 v225, v188, v221, vcc
	s_and_b64 vcc, s[96:97], s[12:13]
	v_readlane_b32 s12, v252, 13
	v_readlane_b32 s13, v252, 14
	v_readlane_b32 s96, v252, 11
	v_fma_f32 v221, -v101, v150, v226
	s_or_b64 s[12:13], s[12:13], s[10:11]
	v_readlane_b32 s97, v252, 12
	v_cndmask_b32_e32 v226, v188, v221, vcc
	s_and_b64 vcc, s[96:97], s[12:13]
	v_readlane_b32 s12, v252, 17
	s_waitcnt lgkmcnt(0)
	v_mfma_f32_16x16x32_bf16 v[228:231], v[232:235], v[84:87], v[228:231]
	v_readlane_b32 s13, v252, 18
	v_readlane_b32 s96, v252, 15
	v_fma_f32 v221, -v101, v151, v227
	s_or_b64 s[12:13], s[12:13], s[10:11]
	v_readlane_b32 s97, v252, 16
	v_cndmask_b32_e32 v227, v188, v221, vcc
	s_and_b64 vcc, s[96:97], s[12:13]
	v_readlane_b32 s12, v252, 21
	v_readlane_b32 s13, v252, 22
	v_readlane_b32 s96, v252, 19
	v_fma_f32 v221, -v101, v152, v228
	s_or_b64 s[12:13], s[12:13], s[10:11]
	v_readlane_b32 s97, v252, 20
	v_cndmask_b32_e32 v236, v188, v221, vcc
	s_and_b64 vcc, s[96:97], s[12:13]
	v_readlane_b32 s12, v252, 25
	v_readlane_b32 s13, v252, 26
	v_readlane_b32 s96, v252, 23
	v_fma_f32 v221, -v101, v153, v229
	s_or_b64 s[12:13], s[12:13], s[10:11]
	v_readlane_b32 s97, v252, 24
	v_cndmask_b32_e32 v237, v188, v221, vcc
	v_fma_f32 v221, -v101, v154, v230
	s_and_b64 vcc, s[96:97], s[12:13]
	v_cndmask_b32_e32 v238, v188, v221, vcc
	v_fma_f32 v221, -v101, v155, v231
	ds_read_b128 v[228:231], v211 offset:34816
	ds_read_b128 v[232:235], v211 offset:34880
	s_waitcnt lgkmcnt(1)
	v_mfma_f32_16x16x32_bf16 v[228:231], v[228:231], v[96:99], 0
	v_readlane_b32 s12, v252, 29
	v_readlane_b32 s13, v252, 30
	v_readlane_b32 s96, v252, 27
	s_waitcnt lgkmcnt(0)
	v_mfma_f32_16x16x32_bf16 v[228:231], v[232:235], v[92:95], v[228:231]
	ds_read_b128 v[232:235], v211 offset:34944
	s_or_b64 s[12:13], s[12:13], s[10:11]
	v_readlane_b32 s97, v252, 28
	s_waitcnt lgkmcnt(0)
	v_mfma_f32_16x16x32_bf16 v[228:231], v[232:235], v[88:91], v[228:231]
	ds_read_b128 v[232:235], v211 offset:35008
	s_and_b64 vcc, s[96:97], s[12:13]
	v_readlane_b32 s12, v252, 33
	s_waitcnt lgkmcnt(0)
	v_mfma_f32_16x16x32_bf16 v[228:231], v[232:235], v[84:87], v[228:231]
	v_readlane_b32 s13, v252, 34
	v_readlane_b32 s96, v252, 31
	s_or_b64 s[12:13], s[12:13], s[10:11]
	v_readlane_b32 s97, v252, 32
	v_cndmask_b32_e32 v239, v188, v221, vcc
	s_and_b64 vcc, s[96:97], s[12:13]
	v_readlane_b32 s12, v252, 37
	v_readlane_b32 s13, v252, 38
	v_readlane_b32 s96, v252, 35
	v_fma_f32 v221, -v101, v156, v228
	s_or_b64 s[12:13], s[12:13], s[10:11]
	v_readlane_b32 s97, v252, 36
	v_cndmask_b32_e32 v240, v188, v221, vcc
	s_and_b64 vcc, s[96:97], s[12:13]
	v_readlane_b32 s12, v252, 41
	v_readlane_b32 s13, v252, 42
	v_readlane_b32 s96, v252, 39
	v_fma_f32 v221, -v101, v157, v229
	s_or_b64 s[12:13], s[12:13], s[10:11]
	v_readlane_b32 s97, v252, 40
	v_cndmask_b32_e32 v241, v188, v221, vcc
	v_fma_f32 v221, -v101, v158, v230
	s_and_b64 vcc, s[96:97], s[12:13]
	v_cndmask_b32_e32 v242, v188, v221, vcc
	v_fma_f32 v221, -v101, v159, v231
	ds_read_b128 v[228:231], v212 offset:34816
	ds_read_b128 v[232:235], v212 offset:34880
	s_waitcnt lgkmcnt(1)
	v_mfma_f32_16x16x32_bf16 v[228:231], v[228:231], v[96:99], 0
	s_or_b64 s[12:13], s[24:25], s[10:11]
	s_and_b64 vcc, s[22:23], s[12:13]
	s_or_b64 s[12:13], s[28:29], s[10:11]
	s_waitcnt lgkmcnt(0)
	v_mfma_f32_16x16x32_bf16 v[228:231], v[232:235], v[92:95], v[228:231]
	ds_read_b128 v[232:235], v212 offset:34944
	v_cndmask_b32_e32 v243, v188, v221, vcc
	s_and_b64 vcc, s[26:27], s[12:13]
	s_waitcnt lgkmcnt(0)
	v_mfma_f32_16x16x32_bf16 v[228:231], v[232:235], v[88:91], v[228:231]
	ds_read_b128 v[232:235], v212 offset:35008
	s_or_b64 s[12:13], s[34:35], s[10:11]
	s_waitcnt lgkmcnt(0)
	s_waitcnt lgkmcnt(0)
	v_mfma_f32_16x16x32_bf16 v[228:231], v[232:235], v[84:87], v[228:231]
	ds_read_b128 v[232:235], v213 offset:34880
	s_nop 6
	v_fma_f32 v221, -v101, v160, v228
	v_cndmask_b32_e32 v244, v188, v221, vcc
	v_fma_f32 v221, -v101, v161, v229
	s_and_b64 vcc, s[30:31], s[12:13]
	s_or_b64 s[12:13], s[4:5], s[10:11]
	v_cndmask_b32_e32 v245, v188, v221, vcc
	v_fma_f32 v221, -v101, v162, v230
	s_and_b64 vcc, s[14:15], s[12:13]
	v_cndmask_b32_e32 v246, v188, v221, vcc
	v_fma_f32 v221, -v101, v163, v231
	ds_read_b128 v[228:231], v213 offset:34816
	s_waitcnt lgkmcnt(0)
	v_mfma_f32_16x16x32_bf16 v[228:231], v[228:231], v[96:99], 0
	s_or_b64 s[12:13], s[2:3], s[10:11]
	s_and_b64 vcc, s[0:1], s[12:13]
	s_or_b64 s[12:13], s[8:9], s[10:11]
	v_mfma_f32_16x16x32_bf16 v[228:231], v[232:235], v[92:95], v[228:231]
	ds_read_b128 v[232:235], v213 offset:34944
	v_cndmask_b32_e32 v247, v188, v221, vcc
	s_and_b64 vcc, s[6:7], s[12:13]
	s_waitcnt lgkmcnt(0)
	v_mfma_f32_16x16x32_bf16 v[228:231], v[232:235], v[88:91], v[228:231]
	ds_read_b128 v[232:235], v213 offset:35008
	s_or_b64 s[12:13], s[40:41], s[10:11]
	s_waitcnt lgkmcnt(0)
	v_mfma_f32_16x16x32_bf16 v[228:231], v[232:235], v[84:87], v[228:231]
	ds_read_b128 v[232:235], v214 offset:34880
	s_nop 6
	v_fma_f32 v221, -v101, v164, v228
	v_cndmask_b32_e32 v248, v188, v221, vcc
	v_fma_f32 v221, -v101, v165, v229
	s_and_b64 vcc, s[16:17], s[12:13]
	s_or_b64 s[12:13], s[44:45], s[10:11]
	v_cndmask_b32_e32 v249, v188, v221, vcc
	v_fma_f32 v221, -v101, v166, v230
	s_and_b64 vcc, s[42:43], s[12:13]
	v_cndmask_b32_e32 v250, v188, v221, vcc
	v_fma_f32 v221, -v101, v167, v231
	ds_read_b128 v[228:231], v214 offset:34816
	s_waitcnt lgkmcnt(0)
; #define LAS __attribute__((address_space(3)))
; __device__ __forceinline__ float shx(float v, int lane, int mask) { return __int_as_float(__builtin_amdgcn_ds_bpermute((lane ^ mask) << 2, __float_as_int(v))); }
; #define MFMA16(a, b, c) __builtin_amdgcn_mfma_f32_16x16x32_bf16((a), (b), (c), 0, 0, 0)
; __device__ __forceinline__ void attn_stream(const int wv, LAS unsigned char* lds, unsigned ldsb, const float* __restrict__ qng, const float* __restrict__ kng, const bf16_t* __restrict__ qkvr, bf16_t* __restrict__ og, float* __restrict__ lse, ...
;     ...
;                 for (int s2 = 0; s2 < 4; ++s2) kf[q][s2] = *(const LAS bf16x8*)(lds + KI + (16 * (w + t3 + q) + li) * PA + (32 * s2 + 8 * g) * 2);
;             asm volatile("s_waitcnt lgkmcnt(0)" ::: "memory");
;             f32x4 a0 = (f32x4){0.f, 0.f, 0.f, 0.f}, a1 = a0, a2 = a0;
; #pragma unroll
;             for (int s2 = 0; s2 < 4; ++s2) { a0 = MFMA16(kf[0][s2], qf[s2], a0); a1 = MFMA16(kf[1][s2], qf[s2], a1); a2 = MFMA16(kf[2][s2], qf[s2], a2); }
;             sc[t3] = a0; sc[t3 + 1] = a1; sc[t3 + 2] = a2;
;         }
;         sc[9] = (f32x4){0.f, 0.f, 0.f, 0.f};
;         const float slope = exp2f(-8.0f * (float)(hh + 1) / 12.0f) * (float)dil;
;         const int qi = 16 * w + li;
;         float mx = -3.0e38f;
; #pragma unroll
;         for (int tt = 0; tt < 9; ++tt)
; #pragma unroll
;             for (int e = 0; e < 4; ++e) {
;                 const int kj = 16 * (w + tt) + 4 * g + e; const int dist = 128 + qi - kj;
;                 const bool valid = (dist >= 0) && (dist <= 128) && (n > 0 || kj >= 128);
;                 const float sv = valid ? sc[tt][e] - slope * (float)dist : -3.0e38f;
;                 sc[tt][e] = sv; mx = fmaxf(mx, sv);
;             }
;         mx = fmaxf(mx, shx(mx, lane, 16)); mx = fmaxf(mx, shx(mx, lane, 32));
;         float den = 0.f;
; #pragma unroll
;         for (int tt = 0; tt < 9; ++tt)
; #pragma unroll
;             for (int e = 0; e < 4; ++e) { const float sv = sc[tt][e]; const float pv = (sv > -1.0e38f) ? __expf(sv - mx) : 0.f; sc[tt][e] = pv; den += pv; }
	v_mfma_f32_16x16x32_bf16 v[228:231], v[228:231], v[96:99], 0
	s_or_b64 s[12:13], s[48:49], s[10:11]
	s_and_b64 vcc, s[46:47], s[12:13]
	s_or_b64 s[12:13], s[52:53], s[10:11]
	v_mfma_f32_16x16x32_bf16 v[228:231], v[232:235], v[92:95], v[228:231]
	ds_read_b128 v[232:235], v214 offset:34944
	v_cndmask_b32_e32 v251, v188, v221, vcc
	s_and_b64 vcc, s[50:51], s[12:13]
	s_waitcnt lgkmcnt(0)
	v_mfma_f32_16x16x32_bf16 v[228:231], v[232:235], v[88:91], v[228:231]
	ds_read_b128 v[232:235], v214 offset:35008
	s_or_b64 s[12:13], s[56:57], s[10:11]
	s_waitcnt lgkmcnt(0)
	v_mfma_f32_16x16x32_bf16 v[228:231], v[232:235], v[84:87], v[228:231]
	s_nop 7
	v_fma_f32 v221, -v101, v168, v228
	v_cndmask_b32_e32 v232, v188, v221, vcc
	v_fma_f32 v221, -v101, v169, v229
	s_and_b64 vcc, s[54:55], s[12:13]
	s_or_b64 s[12:13], s[60:61], s[10:11]
	v_cndmask_b32_e32 v233, v188, v221, vcc
	v_fma_f32 v221, -v101, v170, v230
	s_and_b64 vcc, s[58:59], s[12:13]
	v_cndmask_b32_e32 v234, v188, v221, vcc
	v_fma_f32 v221, -v101, v171, v231
	ds_read_b128 v[228:231], v215 offset:34816
	s_waitcnt lgkmcnt(0)
	v_mfma_f32_16x16x32_bf16 v[96:99], v[228:231], v[96:99], 0
	ds_read_b128 v[228:231], v215 offset:34880
	s_or_b64 s[12:13], s[64:65], s[10:11]
	s_and_b64 vcc, s[62:63], s[12:13]
	s_waitcnt lgkmcnt(0)
	v_mfma_f32_16x16x32_bf16 v[92:95], v[228:231], v[92:95], v[96:99]
	s_nop 2
	ds_read_b128 v[96:99], v215 offset:34944
	s_or_b64 s[12:13], s[68:69], s[10:11]
	v_cndmask_b32_e32 v235, v188, v221, vcc
	s_waitcnt lgkmcnt(0)
	v_mfma_f32_16x16x32_bf16 v[88:91], v[96:99], v[88:91], v[92:95]
	s_nop 2
	ds_read_b128 v[92:95], v215 offset:35008
	s_and_b64 vcc, s[66:67], s[12:13]
	s_or_b64 s[12:13], s[72:73], s[10:11]
	s_waitcnt lgkmcnt(0)
	v_mfma_f32_16x16x32_bf16 v[84:87], v[92:95], v[84:87], v[88:91]
	s_waitcnt lgkmcnt(0)
	s_nop 7
	v_fma_f32 v84, -v101, v172, v84
	v_cndmask_b32_e32 v84, v188, v84, vcc
	v_fma_f32 v85, -v101, v173, v85
	s_and_b64 vcc, s[70:71], s[12:13]
	s_or_b64 s[12:13], s[76:77], s[10:11]
	v_cndmask_b32_e32 v85, v188, v85, vcc
	v_fma_f32 v86, -v101, v174, v86
	s_and_b64 vcc, s[74:75], s[12:13]
	s_or_b64 s[10:11], s[80:81], s[10:11]
	v_cndmask_b32_e32 v86, v188, v86, vcc
	s_and_b64 vcc, s[78:79], s[10:11]
	s_mov_b32 s10, 0xff61b1e6
	v_max3_f32 v88, v1, s10, v2
	v_max3_f32 v88, v88, v3, v100
	v_max3_f32 v88, v88, v102, v103
	v_max3_f32 v88, v88, v222, v223
	v_max3_f32 v88, v88, v224, v225
	v_max3_f32 v88, v88, v226, v227
	v_max3_f32 v88, v88, v236, v237
	v_max3_f32 v88, v88, v238, v239
	v_max3_f32 v88, v88, v240, v241
	v_max3_f32 v88, v88, v242, v243
	v_max3_f32 v88, v88, v244, v245
	v_max3_f32 v88, v88, v246, v247
	v_max3_f32 v88, v88, v248, v249
	v_max3_f32 v88, v88, v250, v251
	v_max3_f32 v88, v88, v232, v233
	v_fma_f32 v87, -v101, v175, v87
	v_max3_f32 v88, v88, v234, v235
	v_cndmask_b32_e32 v87, v188, v87, vcc
	v_max3_f32 v88, v88, v84, v85
	v_max3_f32 v88, v88, v86, v87
	ds_bpermute_b32 v89, v138, v88
	v_cmp_lt_f32_e32 vcc, s37, v1
	v_readlane_b32 s10, v254, 2
	s_add_i32 s82, s82, s10
	s_cmpk_gt_i32 s82, 0x2ff
	s_waitcnt lgkmcnt(0)
	v_max_f32_e32 v89, v89, v89
	v_max_f32_e32 v88, v88, v89
	ds_bpermute_b32 v89, v139, v88
	v_readlane_b32 s11, v254, 3
	s_waitcnt lgkmcnt(0)
	v_max_f32_e32 v89, v89, v89
	v_max_f32_e32 v221, v88, v89
	v_sub_f32_e32 v88, v1, v221
	v_mul_f32_e32 v88, 0x3fb8aa3b, v88
	v_exp_f32_e32 v88, v88
	v_sub_f32_e32 v89, v102, v221
	v_mul_f32_e32 v89, 0x3fb8aa3b, v89
	v_sub_f32_e32 v90, v103, v221
	v_cndmask_b32_e32 v1, 0, v88, vcc
	v_sub_f32_e32 v88, v2, v221
	v_mul_f32_e32 v88, 0x3fb8aa3b, v88
	v_exp_f32_e32 v88, v88
	v_cmp_lt_f32_e32 vcc, s37, v2
	v_exp_f32_e32 v89, v89
	v_mul_f32_e32 v90, 0x3fb8aa3b, v90
	v_cndmask_b32_e32 v2, 0, v88, vcc
	v_sub_f32_e32 v88, v3, v221
	v_mul_f32_e32 v88, 0x3fb8aa3b, v88
	v_exp_f32_e32 v88, v88
	v_cmp_lt_f32_e32 vcc, s37, v3
	v_sub_f32_e32 v91, v222, v221
	v_exp_f32_e32 v90, v90
	v_cndmask_b32_e32 v3, 0, v88, vcc
	v_sub_f32_e32 v88, v100, v221
	v_mul_f32_e32 v88, 0x3fb8aa3b, v88
	v_exp_f32_e32 v88, v88
	v_mul_f32_e32 v91, 0x3fb8aa3b, v91
	v_sub_f32_e32 v92, v223, v221
	v_cmp_lt_f32_e32 vcc, s37, v100
	v_exp_f32_e32 v91, v91
	v_mul_f32_e32 v92, 0x3fb8aa3b, v92
	v_sub_f32_e32 v93, v224, v221
	v_cndmask_b32_e32 v88, 0, v88, vcc
	v_cmp_lt_f32_e32 vcc, s37, v102
	v_exp_f32_e32 v92, v92
	v_mul_f32_e32 v93, 0x3fb8aa3b, v93
	v_sub_f32_e32 v94, v225, v221
	v_cndmask_b32_e32 v89, 0, v89, vcc
	v_cmp_lt_f32_e32 vcc, s37, v103
	v_exp_f32_e32 v93, v93
	v_mul_f32_e32 v94, 0x3fb8aa3b, v94
	v_sub_f32_e32 v95, v226, v221
	v_cndmask_b32_e32 v90, 0, v90, vcc
	v_cmp_lt_f32_e32 vcc, s37, v222
	v_exp_f32_e32 v94, v94
	v_mul_f32_e32 v95, 0x3fb8aa3b, v95
	v_sub_f32_e32 v96, v227, v221
	v_cndmask_b32_e32 v91, 0, v91, vcc
	v_cmp_lt_f32_e32 vcc, s37, v223
	v_exp_f32_e32 v95, v95
	v_mul_f32_e32 v96, 0x3fb8aa3b, v96
	v_cndmask_b32_e32 v92, 0, v92, vcc
	v_cmp_lt_f32_e32 vcc, s37, v224
	v_exp_f32_e32 v96, v96
	s_nop 0
	v_cndmask_b32_e32 v93, 0, v93, vcc
	v_cmp_lt_f32_e32 vcc, s37, v225
	s_nop 1
	v_cndmask_b32_e32 v94, 0, v94, vcc
	v_cmp_lt_f32_e32 vcc, s37, v226
	s_nop 1
	v_cndmask_b32_e32 v95, 0, v95, vcc
	v_cmp_lt_f32_e32 vcc, s37, v227
	s_nop 1
	v_cndmask_b32_e32 v97, 0, v96, vcc
	v_sub_f32_e32 v96, v236, v221
	v_mul_f32_e32 v96, 0x3fb8aa3b, v96
	v_exp_f32_e32 v96, v96
	v_cmp_lt_f32_e32 vcc, s37, v236
	s_nop 1
	v_cndmask_b32_e32 v98, 0, v96, vcc
	v_sub_f32_e32 v96, v237, v221
	v_mul_f32_e32 v96, 0x3fb8aa3b, v96
	v_exp_f32_e32 v96, v96
	v_cmp_lt_f32_e32 vcc, s37, v237
	s_nop 1
	v_cndmask_b32_e32 v99, 0, v96, vcc
	v_sub_f32_e32 v96, v238, v221
	v_mul_f32_e32 v96, 0x3fb8aa3b, v96
	v_exp_f32_e32 v96, v96
	v_cmp_lt_f32_e32 vcc, s37, v238
	s_nop 1
; __device__ __forceinline__ float shx(float v, int lane, int mask) { return __int_as_float(__builtin_amdgcn_ds_bpermute((lane ^ mask) << 2, __float_as_int(v))); }
; __device__ __forceinline__ unsigned cvt_pk_bf16(float lo, float hi) { unsigned r; asm volatile("v_cvt_pk_bf16_f32 %0, %1, %2" : "=v"(r) : "v"(lo), "v"(hi)); return r; }
; __device__ __forceinline__ void attn_stream(const int wv, LAS unsigned char* lds, unsigned ldsb, const float* __restrict__ qng, const float* __restrict__ kng, const bf16_t* __restrict__ qkvr, bf16_t* __restrict__ og, float* __restrict__ lse, ...
;     ...
;         float den = 0.f;
; #pragma unroll
;         for (int tt = 0; tt < 9; ++tt)
; #pragma unroll
;             for (int e = 0; e < 4; ++e) { const float sv = sc[tt][e]; const float pv = (sv > -1.0e38f) ? __expf(sv - mx) : 0.f; sc[tt][e] = pv; den += pv; }
;         den += shx(den, lane, 16); den += shx(den, lane, 32);
;         bf16x8 pf[5];
; #pragma unroll
;         for (int u = 0; u < 5; ++u) { Frag f; f.u.x = cvt_pk_bf16(sc[2 * u][0], sc[2 * u][1]); f.u.y = cvt_pk_bf16(sc[2 * u][2], sc[2 * u][3]); f.u.z = cvt_pk_bf16(sc[2 * u + 1][0], sc[2 * u + 1][1]); f.u.w = cvt_pk_bf16(sc[2 * u + 1][2], sc[2 * u + 1][3]); pf[u] = f.v; }
;         __syncthreads();
	v_cndmask_b32_e32 v224, 0, v96, vcc
	v_sub_f32_e32 v96, v239, v221
	v_mul_f32_e32 v96, 0x3fb8aa3b, v96
	v_exp_f32_e32 v96, v96
	v_cmp_lt_f32_e32 vcc, s37, v239
	s_nop 1
	v_cndmask_b32_e32 v225, 0, v96, vcc
	v_sub_f32_e32 v96, v240, v221
	v_mul_f32_e32 v96, 0x3fb8aa3b, v96
	v_exp_f32_e32 v96, v96
	v_cmp_lt_f32_e32 vcc, s37, v240
	s_nop 1
	v_cndmask_b32_e32 v226, 0, v96, vcc
	v_sub_f32_e32 v96, v241, v221
	v_mul_f32_e32 v96, 0x3fb8aa3b, v96
	v_exp_f32_e32 v96, v96
	v_cmp_lt_f32_e32 vcc, s37, v241
	s_nop 1
	v_cndmask_b32_e32 v227, 0, v96, vcc
	v_sub_f32_e32 v96, v242, v221
	v_mul_f32_e32 v96, 0x3fb8aa3b, v96
	v_exp_f32_e32 v96, v96
	v_cmp_lt_f32_e32 vcc, s37, v242
	s_nop 1
	v_cndmask_b32_e32 v228, 0, v96, vcc
	v_sub_f32_e32 v96, v243, v221
	v_mul_f32_e32 v96, 0x3fb8aa3b, v96
	v_exp_f32_e32 v96, v96
	v_cmp_lt_f32_e32 vcc, s37, v243
	s_nop 1
	v_cndmask_b32_e32 v229, 0, v96, vcc
	v_sub_f32_e32 v96, v244, v221
	v_mul_f32_e32 v96, 0x3fb8aa3b, v96
	v_exp_f32_e32 v96, v96
	v_cmp_lt_f32_e32 vcc, s37, v244
	s_nop 1
	v_cndmask_b32_e32 v230, 0, v96, vcc
	v_sub_f32_e32 v96, v245, v221
	v_mul_f32_e32 v96, 0x3fb8aa3b, v96
	v_exp_f32_e32 v96, v96
	v_cmp_lt_f32_e32 vcc, s37, v245
	s_nop 1
	v_cndmask_b32_e32 v231, 0, v96, vcc
	v_sub_f32_e32 v96, v246, v221
	v_mul_f32_e32 v96, 0x3fb8aa3b, v96
	v_exp_f32_e32 v96, v96
	v_cmp_lt_f32_e32 vcc, s37, v246
	s_nop 1
	v_cndmask_b32_e32 v236, 0, v96, vcc
	v_sub_f32_e32 v96, v247, v221
	v_mul_f32_e32 v96, 0x3fb8aa3b, v96
	v_exp_f32_e32 v96, v96
	v_cmp_lt_f32_e32 vcc, s37, v247
	s_nop 1
	v_cndmask_b32_e32 v237, 0, v96, vcc
	v_sub_f32_e32 v96, v248, v221
	v_mul_f32_e32 v96, 0x3fb8aa3b, v96
	v_exp_f32_e32 v96, v96
	v_cmp_lt_f32_e32 vcc, s37, v248
	s_nop 1
	v_cndmask_b32_e32 v238, 0, v96, vcc
	v_sub_f32_e32 v96, v249, v221
	v_mul_f32_e32 v96, 0x3fb8aa3b, v96
	v_exp_f32_e32 v96, v96
	v_cmp_lt_f32_e32 vcc, s37, v249
	s_nop 1
	v_cndmask_b32_e32 v239, 0, v96, vcc
	v_sub_f32_e32 v96, v250, v221
	v_mul_f32_e32 v96, 0x3fb8aa3b, v96
	v_exp_f32_e32 v96, v96
	v_cmp_lt_f32_e32 vcc, s37, v250
	s_nop 1
	v_cndmask_b32_e32 v240, 0, v96, vcc
	v_sub_f32_e32 v96, v251, v221
	v_mul_f32_e32 v96, 0x3fb8aa3b, v96
	v_exp_f32_e32 v96, v96
	v_cmp_lt_f32_e32 vcc, s37, v251
	s_nop 1
	v_cndmask_b32_e32 v241, 0, v96, vcc
	v_sub_f32_e32 v96, v232, v221
	v_mul_f32_e32 v96, 0x3fb8aa3b, v96
	v_exp_f32_e32 v96, v96
	v_cmp_lt_f32_e32 vcc, s37, v232
	s_nop 1
	v_cndmask_b32_e32 v232, 0, v96, vcc
	v_sub_f32_e32 v96, v233, v221
	v_mul_f32_e32 v96, 0x3fb8aa3b, v96
	v_exp_f32_e32 v96, v96
	v_cmp_lt_f32_e32 vcc, s37, v233
	s_nop 1
	v_cndmask_b32_e32 v233, 0, v96, vcc
	v_sub_f32_e32 v96, v234, v221
	v_mul_f32_e32 v96, 0x3fb8aa3b, v96
	v_exp_f32_e32 v96, v96
	v_cmp_lt_f32_e32 vcc, s37, v234
	s_nop 1
	v_cndmask_b32_e32 v234, 0, v96, vcc
	v_sub_f32_e32 v96, v235, v221
	v_mul_f32_e32 v96, 0x3fb8aa3b, v96
	v_exp_f32_e32 v96, v96
	v_cmp_lt_f32_e32 vcc, s37, v235
	s_nop 1
	v_cndmask_b32_e32 v235, 0, v96, vcc
	v_sub_f32_e32 v96, v84, v221
	v_mul_f32_e32 v96, 0x3fb8aa3b, v96
	v_exp_f32_e32 v96, v96
	v_cmp_lt_f32_e32 vcc, s37, v84
	s_nop 1
	v_cndmask_b32_e32 v84, 0, v96, vcc
	v_sub_f32_e32 v96, v85, v221
	v_mul_f32_e32 v96, 0x3fb8aa3b, v96
	v_exp_f32_e32 v96, v96
	v_cmp_lt_f32_e32 vcc, s37, v85
	s_nop 1
	v_cndmask_b32_e32 v85, 0, v96, vcc
	v_sub_f32_e32 v96, v86, v221
	v_mul_f32_e32 v96, 0x3fb8aa3b, v96
	v_exp_f32_e32 v96, v96
	v_cmp_lt_f32_e32 vcc, s37, v86
	s_nop 1
	v_cndmask_b32_e32 v86, 0, v96, vcc
	v_sub_f32_e32 v96, v87, v221
	v_mul_f32_e32 v96, 0x3fb8aa3b, v96
	v_exp_f32_e32 v96, v96
	v_cmp_lt_f32_e32 vcc, s37, v87
	s_nop 1
	v_cndmask_b32_e32 v87, 0, v96, vcc
	v_add_f32_e32 v96, 0, v1
	v_add_f32_e32 v96, v2, v96
	v_add_f32_e32 v96, v3, v96
	v_add_f32_e32 v96, v88, v96
	v_add_f32_e32 v96, v89, v96
	v_add_f32_e32 v96, v90, v96
	v_add_f32_e32 v96, v91, v96
	v_add_f32_e32 v96, v92, v96
	v_add_f32_e32 v96, v93, v96
	v_add_f32_e32 v96, v94, v96
	v_add_f32_e32 v96, v95, v96
	v_add_f32_e32 v96, v97, v96
	v_add_f32_e32 v96, v98, v96
	v_add_f32_e32 v96, v99, v96
	v_add_f32_e32 v96, v224, v96
	v_add_f32_e32 v96, v225, v96
	v_add_f32_e32 v96, v226, v96
	v_add_f32_e32 v96, v227, v96
	v_add_f32_e32 v96, v228, v96
	v_add_f32_e32 v96, v229, v96
	v_add_f32_e32 v96, v230, v96
	v_add_f32_e32 v96, v231, v96
	v_add_f32_e32 v96, v236, v96
	v_add_f32_e32 v96, v237, v96
	v_add_f32_e32 v96, v238, v96
	v_add_f32_e32 v96, v239, v96
	v_add_f32_e32 v96, v240, v96
	v_add_f32_e32 v96, v241, v96
	v_add_f32_e32 v96, v232, v96
	v_add_f32_e32 v96, v233, v96
	v_add_f32_e32 v96, v234, v96
	v_add_f32_e32 v96, v235, v96
	v_add_f32_e32 v96, v84, v96
	v_add_f32_e32 v96, v85, v96
	v_add_f32_e32 v96, v86, v96
	v_add_f32_e32 v96, v87, v96
	ds_bpermute_b32 v100, v138, v96
	s_waitcnt lgkmcnt(0)
	v_add_f32_e32 v222, v96, v100
	ds_bpermute_b32 v223, v139, v222
	v_cvt_pk_bf16_f32 v100, v1, v2
	v_cvt_pk_bf16_f32 v101, v3, v88
	v_cvt_pk_bf16_f32 v102, v89, v90
	v_cvt_pk_bf16_f32 v103, v91, v92
	v_cvt_pk_bf16_f32 v96, v93, v94
	v_cvt_pk_bf16_f32 v97, v95, v97
	v_cvt_pk_bf16_f32 v98, v98, v99
	v_cvt_pk_bf16_f32 v99, v224, v225
	v_cvt_pk_bf16_f32 v92, v226, v227
	v_cvt_pk_bf16_f32 v93, v228, v229
	v_cvt_pk_bf16_f32 v94, v230, v231
	v_cvt_pk_bf16_f32 v95, v236, v237
	v_cvt_pk_bf16_f32 v88, v238, v239
	v_cvt_pk_bf16_f32 v89, v240, v241
	v_cvt_pk_bf16_f32 v90, v232, v233
	v_cvt_pk_bf16_f32 v91, v234, v235
	v_cvt_pk_bf16_f32 v84, v84, v85
	v_cvt_pk_bf16_f32 v85, v86, v87
	v_cvt_pk_bf16_f32 v86, v0, v0
	v_cvt_pk_bf16_f32 v87, v0, v0
	s_waitcnt lgkmcnt(0)
	s_barrier
; #define LAS __attribute__((address_space(3)))
; __device__ __forceinline__ void attn_stream(const int wv, LAS unsigned char* lds, unsigned ldsb, const float* __restrict__ qng, const float* __restrict__ kng, const bf16_t* __restrict__ qkvr, bf16_t* __restrict__ og, float* __restrict__ lse, ...
;     ...
;         for (int it = 0; it < 8; ++it) *(LAS u32x4*)(lds + KI + (rr + 32 * it) * PA + c16 * 16) = vr[it];
;         __syncthreads();
;         if (inext < count) ATTN_LOAD_QK(inext);
	s_waitcnt vmcnt(0)
	ds_write_b128 v108, v[56:59] offset:34816
	ds_write_b128 v108, v[60:63] offset:43520
	ds_write_b128 v108, v[52:55] offset:52224
	ds_write_b128 v108, v[68:71] offset:60928
	ds_write_b128 v109, v[64:67] offset:34816
	ds_write_b128 v109, v[76:79] offset:43520
	ds_write_b128 v109, v[72:75] offset:52224
	ds_write_b128 v109, v[80:83] offset:60928
	s_waitcnt lgkmcnt(0)
	s_barrier
	s_cbranch_scc1 .LBB0_363
	s_and_b32 s10, s82, 63
	s_and_b32 s11, s82, 0xffffff00
	s_cmpk_eq_i32 s11, 0x100
	s_cselect_b32 s11, 2, 4
	s_cmpk_gt_u32 s82, 0xff
	s_cselect_b32 s21, s11, 0
	s_lshr_b32 s11, 64, s21
	s_xor_b32 s12, s21, 6
	s_add_i32 s11, s11, -1
	s_lshr_b32 s95, s10, s12
	s_and_b32 s10, s11, s10
	v_mov_b32_e32 v1, v130
	v_mov_b32_e32 v2, v105
	v_lshl_add_u32 v36, s10, 7, v1
	s_and_b32 s10, s39, 0xffffff80
	s_ashr_i32 s11, s10, 31
	v_lshlrev_b32_e32 v1, s21, v36
	s_lshl_b64 s[12:13], s[10:11], 1
	v_add_u32_e32 v40, s95, v1
	v_add_lshl_u32 v1, v36, 32, s21
	s_add_u32 s12, s90, s12
	v_lshlrev_b32_e32 v52, 3, v2
	v_add_u32_e32 v44, s95, v1
	v_add_lshl_u32 v1, v36, 64, s21
	s_addc_u32 s13, s91, s13
	v_ashrrev_i32_e32 v53, 31, v52
	v_add_u32_e32 v48, s95, v1
	v_add_u32_e32 v1, 0x60, v36
	v_lshl_add_u64 v[2:3], v[52:53], 1, s[12:13]
	v_lshlrev_b32_e32 v1, s21, v1
	v_mad_i64_i32 v[4:5], s[12:13], v40, s33, v[2:3]
	v_mad_i64_i32 v[8:9], s[12:13], v44, s33, v[2:3]
	v_mad_i64_i32 v[12:13], s[12:13], v48, s33, v[2:3]
	v_add_u32_e32 v54, s95, v1
	global_load_dwordx4 v[4:7], v[4:5], off
	s_nop 0
	global_load_dwordx4 v[8:11], v[8:9], off
	v_mad_i64_i32 v[2:3], s[12:13], v54, s33, v[2:3]
	global_load_dwordx4 v[12:15], v[12:13], off
	s_nop 0
	global_load_dwordx4 v[16:19], v[2:3], off
	v_mov_b32_e32 v22, v0
	v_mov_b32_e32 v23, v0
	v_add_u32_e32 v49, 0xffffff80, v36
	v_mov_b32_e32 v20, v0
	v_mov_b32_e32 v21, v0
	v_mov_b64_e32 v[26:27], v[22:23]
	v_cmp_lt_i32_e32 vcc, -1, v49
	v_mov_b64_e32 v[24:25], v[20:21]
	s_and_saveexec_b64 s[12:13], vcc
	s_cbranch_execz .LBB0_348
	v_lshlrev_b32_e32 v1, s21, v49
	v_add_u32_e32 v1, s95, v1
	v_mov_b64_e32 v[2:3], s[90:91]
	v_mad_u64_u32 v[2:3], s[96:97], v1, s33, v[2:3]
	v_lshl_add_u64 v[2:3], s[10:11], 1, v[2:3]
	v_lshl_add_u64 v[2:3], v[52:53], 1, v[2:3]
	global_load_dwordx4 v[24:27], v[2:3], off offset:3072

; __device__ __forceinline__ KParams kparams() { unsigned long long a = (unsigned long long)__builtin_amdgcn_kernarg_segment_ptr(); asm volatile("" : "+s"(a)); return (KParams)a; }
; #define GSYNC() xcd_barrier(wv, xb)
; __global__ void __launch_bounds__(512, 2) mega(Params p_unused) {
;     ...
;             attn_stream(wv, lds, ldsb, kp->q_norm_g, kp->k_norm_g, WSP(bf16_t, WS_R0), WSP(bf16_t, WS_OG), WSP(float, WS_LSE), (int)blockIdx.x, (int)gridDim.x, 768);
;         }
;         {
;             KParams kp = kparams(); unsigned char* ws = kp->ws;
;             for (int j = blockIdx.x; j < 512; j += gridDim.x) reta_item(wv, lds, ldsb, WSP(bf16_t, WS_R0), WSP(bf16_t, WS_KV), j);
;         }
;         GSYNC();
;         { KParams kp = kparams(); unsigned char* ws = kp->ws; ret_scan(wv, WSP(bf16_t, WS_KV)); }
.LBB0_365:
	v_readlane_b32 s66, v254, 0
	v_readlane_b32 s54, v254, 2
	v_readlane_b32 s56, v254, 4
	v_readlane_b32 s58, v254, 7
	v_readlane_b32 s64, v254, 12
	v_readlane_b32 s80, v254, 27
	v_readlane_b32 s67, v254, 1
	v_readlane_b32 s55, v254, 3
	v_readlane_b32 s57, v254, 5
	v_readlane_b32 s53, v254, 6
	v_readlane_b32 s59, v254, 8
	v_readlane_b32 s61, v254, 9
	v_readlane_b32 s60, v254, 10
	v_readlane_b32 s62, v254, 11
	v_readlane_b32 s65, v254, 13
	v_readlane_b32 s63, v254, 14
	v_readlane_b32 s68, v254, 15
	s_movk_i32 s69, 0xa9
	v_readlane_b32 s70, v254, 16
	v_readlane_b32 s71, v254, 17
	s_movk_i32 s72, 0x2000
	s_movk_i32 s76, 0x7f
	v_readlane_b32 s73, v254, 18
	v_readlane_b32 s74, v254, 19
	s_movk_i32 s75, 0x3000
	v_readlane_b32 s77, v254, 20
	s_mov_b32 s78, 0x80000
	v_readlane_b32 s79, v254, 26
	v_readlane_b32 s81, v254, 28
.Latt_done:
	s_cmp_eq_u32 s101, 0
	s_cbranch_scc1 .Lgwsc_done
	v_mov_b32_e32 v222, s98
	v_mov_b32_e32 v223, s99

; __device__ __forceinline__ unsigned xb_ld(unsigned* p)              { return __hip_atomic_load(p, __ATOMIC_RELAXED, __HIP_MEMORY_SCOPE_AGENT); }
; __device__ __forceinline__ unsigned xb_add(unsigned* p, unsigned v) { return __hip_atomic_fetch_add(p, v, __ATOMIC_RELAXED, __HIP_MEMORY_SCOPE_AGENT); }
; #define XB_SPIN(cond, bar) do { unsigned _sp = 0; while (cond) { __builtin_amdgcn_s_sleep(1); \
;     if ((++_sp & 255u) == 0u) { if (xb_ld(&(bar)[XB_TMO])) break; if (_sp > XB_SPIN_CAP) { atomicAdd(&(bar)[XB_TMO], 1u); break; } } } } while (0)
; __device__ __forceinline__ void ret_scan(const int wv, bf16_t* __restrict__ kv) {
;     int ts_ = TIDX; asm volatile("" : "+v"(ts_));
;     for (int idx = blockIdx.x * 512 + ts_; idx < 4 * 32768; idx += gridDim.x * 512) {
;         const int h = idx >> 15, e4 = idx & 32767;
;         const float gC = exp2f(128.0f * log2f(1.0f - exp2f(-5.0f - (float)h)));
;         bf16_t* pbase = kv + (size_t)h * 64 * 131072 + (size_t)e4 * 4;
; __device__ __forceinline__ void xcd_barrier(const int wv, const XcdBarrier& b) {
;     ...
;         const unsigned old = xb_add(&bar[XB_XSUB(b.x)], 1u);
;         const unsigned gen = old / nloc;
;         if (old + 1u == (gen + 1u) * nloc) {
;             __builtin_amdgcn_fence(__ATOMIC_RELEASE, "agent");
;             asm volatile("s_waitcnt vmcnt(0)" ::: "memory");
;             const unsigned og = xb_add(&bar[XB_TOP], 1u);
;             const unsigned tg = og / nx;
;             if (og + 1u == (tg + 1u) * nx) xb_add(&bar[XB_TOPGEN], 1u);
;             else XB_SPIN(xb_ld(&bar[XB_TOPGEN]) == tg, bar);
;             __builtin_amdgcn_fence(__ATOMIC_ACQUIRE, "agent");
;             xb_add(&bar[XB_XGEN(b.x)], 1u);
;             asm volatile("s_waitcnt vmcnt(0)" ::: "memory");
.Lgwsc_done:
	s_mov_b64 s[2:3], s[56:57]
	s_waitcnt lgkmcnt(0)
	s_barrier
	v_mbcnt_lo_u32_b32 v1, -1, 0
	v_mbcnt_hi_u32_b32 v1, -1, v1
	s_mov_b32 s0, 0x20000
	v_add_u32_e32 v2, s53, v1
	s_nop 0
	v_add_u32_e32 v1, s63, v2
	v_cmp_gt_i32_e32 vcc, s0, v1
	s_and_saveexec_b64 s[0:1], vcc
	s_cbranch_execz .LBB0_422
	s_load_dwordx2 s[2:3], s[2:3], 0x70
	v_readlane_b32 s4, v253, 51
	s_waitcnt lgkmcnt(0)
	s_add_u32 s2, s2, 0x4dc0000
	s_waitcnt vmcnt(0)
	v_lshl_add_u32 v10, v2, 2, s4
	s_addc_u32 s3, s3, 0
	s_mov_b64 s[4:5], 0
